# scan: stage 4/5 operand-read hoisting, stage 1 LoRA-value prefetch, stage 3 masked stores as straight-line code (was a 30-block branch chain)
# speedup vs baseline: 1.0350x; 1.0089x over previous
.Lrs0_done_515:
	s_nop 3
	s_movk_i32 s5, 0x240
	v_lshlrev_b32_e32 v4, 1, v4
	v_mul_lo_u32 v3, v3, s5
	v_readlane_b32 s5, v253, 60
	s_lshl_b32 s4, s85, 5
	s_nop 0
	v_add3_u32 v3, s5, v4, v3
	v_cvt_pk_bf16_f32 v4, v22, v2
	ds_write_b16 v3, v4
	v_cvt_pk_bf16_f32 v4, v23, v2
	ds_write_b16 v3, v4 offset:144
	v_cvt_pk_bf16_f32 v4, v24, v2
	ds_write_b16 v3, v4 offset:288
	v_cvt_pk_bf16_f32 v4, v25, v2
	ds_write_b16 v3, v4 offset:432
	v_cvt_pk_bf16_f32 v4, v26, v2
	ds_write_b16 v3, v4 offset:1152
	v_cvt_pk_bf16_f32 v4, v27, v2
	ds_write_b16 v3, v4 offset:1296
	v_cvt_pk_bf16_f32 v4, v28, v2
	ds_write_b16 v3, v4 offset:1440
	v_cvt_pk_bf16_f32 v4, v29, v2
	ds_write_b16 v3, v4 offset:1584
	v_cvt_pk_bf16_f32 v4, v30, v2
	ds_write_b16 v3, v4 offset:2304
	v_cvt_pk_bf16_f32 v4, v31, v2
	ds_write_b16 v3, v4 offset:2448
	v_cvt_pk_bf16_f32 v4, v32, v2
	ds_write_b16 v3, v4 offset:2592
	v_cvt_pk_bf16_f32 v4, v33, v2
	ds_write_b16 v3, v4 offset:2736
	v_cvt_pk_bf16_f32 v4, v34, v2
	ds_write_b16 v3, v4 offset:3456
	v_cvt_pk_bf16_f32 v4, v35, v2
	s_add_i32 s5, s4, s73
	ds_write_b16 v3, v4 offset:3600
	v_cvt_pk_bf16_f32 v4, v36, v2
	s_cmp_lt_i32 s5, s82
	ds_write_b16 v3, v4 offset:3744
	v_cvt_pk_bf16_f32 v4, v37, v2
	ds_write_b16 v3, v4 offset:3888
	s_waitcnt lgkmcnt(0)
	s_barrier
	v_add_u32_e32 v208, s33, v109
	v_add_u32_e32 v209, s33, v110
	v_add_u32_e32 v210, s33, v111
	v_add_u32_e32 v211, s91, v109
	v_add_u32_e32 v212, s91, v110
	v_add_u32_e32 v213, s91, v111
	ds_read_u16 v216, v208
	ds_read_u16 v217, v209
	ds_read_u16 v218, v210
	ds_read_u16 v219, v211
	ds_read_u16 v220, v212
	ds_read_u16 v221, v213
	ds_read_u16 v222, v211 offset:144
	ds_read_u16 v223, v212 offset:144
	ds_read_u16 v224, v213 offset:144
	ds_read_u16 v225, v211 offset:288
	ds_read_u16 v226, v212 offset:288
	ds_read_u16 v227, v213 offset:288
	s_waitcnt lgkmcnt(0)
	s_cbranch_scc0 .LBB0_518
	v_add_u32_e32 v4, s33, v109
	v_add_u32_e32 v23, s33, v110
	v_mov_b32_e32 v4, v216
	v_mov_b32_e32 v23, v217
	v_lshlrev_b32_e32 v3, 16, v131
	v_mul_f32_e32 v26, v145, v3
	v_lshlrev_b32_e32 v30, 16, v130
	v_lshlrev_b32_e32 v4, 16, v4
	v_lshlrev_b32_e32 v23, 16, v23
	v_add_f32_e32 v23, v144, v23
	v_mul_f32_e32 v23, 0xbfb8aa3b, v23
	v_exp_f32_e32 v23, v23
	v_add_f32_e32 v4, v143, v4
	v_mul_f32_e32 v4, 0xbfb8aa3b, v4
	v_exp_f32_e32 v4, v4
	v_add_f32_e32 v23, 1.0, v23
	v_rcp_f32_e32 v23, v23
	s_add_i32 s28, s5, s84
	s_ashr_i32 s29, s28, 31
	v_add_f32_e32 v4, 1.0, v4
	v_add_f32_e32 v24, -1.0, v23
	v_fma_f32 v24, v146, v24, 1.0
	v_mul_f32_e32 v31, v24, v3
	v_mul_f32_e32 v3, v26, v26
	v_mul_f32_e32 v24, v31, v30
	v_mul_f32_e32 v25, v147, v24
	v_mov_b32_dpp v3, v3 quad_perm:[1,0,3,2] row_mask:0xf bank_mask:0xf bound_ctrl:1
	v_fmac_f32_e32 v3, v26, v26
	v_mov_b32_dpp v25, v25 quad_perm:[1,0,3,2] row_mask:0xf bank_mask:0xf bound_ctrl:1
	v_fmac_f32_e32 v25, v147, v24
	v_add_f32_dpp v3, v3, v3 quad_perm:[2,3,0,1] row_mask:0xf bank_mask:0xf bound_ctrl:1
	s_lshl_b64 s[28:29], s[28:29], 12
	v_add_f32_dpp v24, v25, v25 quad_perm:[2,3,0,1] row_mask:0xf bank_mask:0xf bound_ctrl:1
	v_add_f32_dpp v3, v3, v3 row_ror:4 row_mask:0xf bank_mask:0xf bound_ctrl:1
	v_rcp_f32_e32 v22, v4
	v_add_f32_dpp v24, v24, v24 row_ror:4 row_mask:0xf bank_mask:0xf bound_ctrl:1
	v_add_f32_dpp v3, v3, v3 row_ror:8 row_mask:0xf bank_mask:0xf bound_ctrl:1
	v_lshl_add_u64 v[4:5], v[92:93], 0, s[28:29]
	v_readlane_b32 s5, v3, 16
	v_readlane_b32 s30, v3, 48
	v_add_f32_dpp v27, v24, v24 row_ror:8 row_mask:0xf bank_mask:0xf bound_ctrl:1
	v_readlane_b32 s28, v3, 0
	v_readlane_b32 s29, v3, 32
	v_mov_b32_e32 v24, s5
	v_mov_b32_e32 v25, s30
	v_pk_add_f32 v[24:25], s[28:29], v[24:25]
	v_readlane_b32 s5, v27, 16
	v_readlane_b32 s30, v27, 48
	v_add_f32_e32 v28, v24, v25
	v_readlane_b32 s28, v27, 0
	v_readlane_b32 s29, v27, 32
	v_mov_b32_e32 v24, s5
	v_mov_b32_e32 v25, s30
	v_pk_add_f32 v[24:25], s[28:29], v[24:25]
	s_nop 0
	v_add_f32_e32 v3, v24, v25
	v_sqrt_f32_e32 v24, v28
	v_lshlrev_b32_e32 v25, 16, v138
	global_store_dword v[4:5], v25, off
	v_xor_b32_e32 v24, 0x80000000, v24
	v_min_f32_e32 v24, 0xab8cbccc, v24
	v_rcp_f32_e32 v24, v24
	s_nop 0
	v_mul_f32_e32 v32, v26, v24
	v_add_u32_e32 v24, s33, v111
	v_mov_b32_e32 v24, v218
	v_xor_b32_e32 v83, 0x80000000, v32
	v_pk_mul_f32 v[22:23], v[22:23], v[82:83]
	v_lshlrev_b32_e32 v24, 16, v24
	s_branch .LBB0_519

.LBB0_519:
	s_and_b32 s5, s85, 1
	s_cmp_eq_u32 s5, 0
	s_movk_i32 s8, 0x6c00
	s_cselect_b32 s90, s8, 0x13600
	s_mov_b32 s8, 0x9000
	s_cselect_b32 s28, s8, 0x14800
	v_readlane_b32 s8, v250, 19
	v_add_u32_e32 v27, s90, v108
	s_lshl_b32 s5, s5, 7
	v_add_u32_e32 v4, s8, v106
	v_add_u32_e32 v26, s28, v108
	s_add_i32 s5, s5, 0
	ds_write_b32 v4, v22 offset:62464
	v_add_u32_e32 v4, s33, v27
	s_add_i32 s5, s5, 0x13500
	v_cvt_pk_bf16_f32 v5, v25, v2
	ds_write_b16 v4, v5
	v_add_u32_e32 v4, s33, v26
	v_cvt_pk_bf16_f32 v5, v24, v2
	ds_write_b16 v4, v5
	s_and_saveexec_b64 s[28:29], s[26:27]
	s_lshl_b32 s30, s73, 2
	s_add_i32 s30, s5, s30
	v_mov_b32_e32 v4, s30
	ds_write_b32 v4, v3
	s_or_b64 exec, exec, s[28:29]
	s_add_i32 s28, s4, s83
	s_cmp_ge_i32 s28, s82
	v_add_u32_e32 v29, s91, v109
	v_add_u32_e32 v28, s91, v110
	v_add_u32_e32 v3, s91, v111
	s_cbranch_scc1 .LBB0_523
	v_mov_b32_e32 v4, v219
	v_mov_b32_e32 v25, v220
	v_lshlrev_b32_e32 v34, 16, v133
	v_mul_f32_e32 v35, v145, v34
	v_lshlrev_b32_e32 v33, 16, v132
	v_lshlrev_b32_e32 v4, 16, v4
	v_lshlrev_b32_e32 v25, 16, v25
	v_add_f32_e32 v25, v144, v25
	v_mul_f32_e32 v25, 0xbfb8aa3b, v25
	v_exp_f32_e32 v25, v25
	v_add_f32_e32 v4, v143, v4
	v_mul_f32_e32 v4, 0xbfb8aa3b, v4
	v_exp_f32_e32 v4, v4
	v_add_f32_e32 v25, 1.0, v25
	v_rcp_f32_e32 v25, v25
	s_add_i32 s28, s28, s84
	s_ashr_i32 s29, s28, 31
	v_add_f32_e32 v4, 1.0, v4
	v_add_f32_e32 v36, -1.0, v25
	v_fma_f32 v36, v146, v36, 1.0
	v_mul_f32_e32 v34, v36, v34
	v_mul_f32_e32 v36, v35, v35
	v_mul_f32_e32 v37, v34, v33
	v_mul_f32_e32 v38, v147, v37
	v_mov_b32_dpp v36, v36 quad_perm:[1,0,3,2] row_mask:0xf bank_mask:0xf bound_ctrl:1
	v_fmac_f32_e32 v36, v35, v35
	v_mov_b32_dpp v38, v38 quad_perm:[1,0,3,2] row_mask:0xf bank_mask:0xf bound_ctrl:1
	v_fmac_f32_e32 v38, v147, v37
	v_add_f32_dpp v36, v36, v36 quad_perm:[2,3,0,1] row_mask:0xf bank_mask:0xf bound_ctrl:1
	s_lshl_b64 s[28:29], s[28:29], 12
	v_add_f32_dpp v37, v38, v38 quad_perm:[2,3,0,1] row_mask:0xf bank_mask:0xf bound_ctrl:1
	v_add_f32_dpp v36, v36, v36 row_ror:4 row_mask:0xf bank_mask:0xf bound_ctrl:1
	v_rcp_f32_e32 v24, v4
	v_add_f32_dpp v37, v37, v37 row_ror:4 row_mask:0xf bank_mask:0xf bound_ctrl:1
	v_add_f32_dpp v36, v36, v36 row_ror:8 row_mask:0xf bank_mask:0xf bound_ctrl:1
	v_lshl_add_u64 v[4:5], v[92:93], 0, s[28:29]
	v_readlane_b32 s30, v36, 16
	v_readlane_b32 s31, v36, 48
	v_add_f32_dpp v38, v37, v37 row_ror:8 row_mask:0xf bank_mask:0xf bound_ctrl:1
	v_readlane_b32 s28, v36, 0
	v_readlane_b32 s29, v36, 32
	v_mov_b32_e32 v36, s30
	v_mov_b32_e32 v37, s31
	v_pk_add_f32 v[36:37], s[28:29], v[36:37]
	v_readlane_b32 s30, v38, 16
	v_readlane_b32 s31, v38, 48
	v_add_f32_e32 v39, v36, v37
	v_readlane_b32 s28, v38, 0
	v_readlane_b32 s29, v38, 32
	v_mov_b32_e32 v36, s30
	v_mov_b32_e32 v37, s31
	v_pk_add_f32 v[36:37], s[28:29], v[36:37]
	v_lshlrev_b32_e32 v38, 16, v139
	v_add_f32_e32 v36, v36, v37
	v_sqrt_f32_e32 v37, v39
	global_store_dword v[4:5], v38, off
	v_xor_b32_e32 v37, 0x80000000, v37
	v_min_f32_e32 v37, 0xab8cbccc, v37
	v_rcp_f32_e32 v37, v37
	s_nop 0
	v_mul_f32_e32 v35, v35, v37
	v_mov_b32_e32 v37, v221
	v_xor_b32_e32 v83, 0x80000000, v35
	v_pk_mul_f32 v[24:25], v[24:25], v[82:83]
	v_lshlrev_b32_e32 v37, 16, v37
	s_branch .LBB0_524

.LBB0_524:
	v_readlane_b32 s8, v250, 20
	v_add_u32_e32 v42, s91, v27
	v_add_u32_e32 v43, s91, v26
	v_add_u32_e32 v4, s8, v106
	ds_write_b32 v4, v24 offset:62464
	v_cvt_pk_bf16_f32 v4, v38, v2
	ds_write_b16 v42, v4
	v_cvt_pk_bf16_f32 v4, v37, v2
	ds_write_b16 v43, v4
	s_and_saveexec_b64 s[28:29], s[26:27]
	s_lshl_b32 s30, s73, 2
	s_add_i32 s30, s5, s30
	v_mov_b32_e32 v4, s30
	ds_write_b32 v4, v36 offset:4
	s_or_b64 exec, exec, s[28:29]
	s_add_i32 s28, s4, s88
	s_cmp_ge_i32 s28, s82
	s_cbranch_scc1 .LBB0_528
	v_mov_b32_e32 v4, v222
	v_mov_b32_e32 v27, v223
	v_lshlrev_b32_e32 v37, 16, v135
	v_mul_f32_e32 v40, v145, v37
	v_lshlrev_b32_e32 v36, 16, v134
	v_lshlrev_b32_e32 v4, 16, v4
	v_lshlrev_b32_e32 v27, 16, v27
	v_add_f32_e32 v27, v144, v27
	v_mul_f32_e32 v27, 0xbfb8aa3b, v27
	v_exp_f32_e32 v27, v27
	v_add_f32_e32 v4, v143, v4
	v_mul_f32_e32 v4, 0xbfb8aa3b, v4
	v_exp_f32_e32 v4, v4
	v_add_f32_e32 v27, 1.0, v27
	v_rcp_f32_e32 v27, v27
	s_add_i32 s28, s28, s84
	s_ashr_i32 s29, s28, 31
	v_add_f32_e32 v4, 1.0, v4
	v_add_f32_e32 v38, -1.0, v27
	v_fma_f32 v38, v146, v38, 1.0
	v_mul_f32_e32 v37, v38, v37
	v_mul_f32_e32 v38, v40, v40
	v_mul_f32_e32 v39, v37, v36
	v_mul_f32_e32 v41, v147, v39
	v_mov_b32_dpp v38, v38 quad_perm:[1,0,3,2] row_mask:0xf bank_mask:0xf bound_ctrl:1
	v_fmac_f32_e32 v38, v40, v40
	v_mov_b32_dpp v41, v41 quad_perm:[1,0,3,2] row_mask:0xf bank_mask:0xf bound_ctrl:1
	v_fmac_f32_e32 v41, v147, v39
	v_add_f32_dpp v38, v38, v38 quad_perm:[2,3,0,1] row_mask:0xf bank_mask:0xf bound_ctrl:1
	s_lshl_b64 s[28:29], s[28:29], 12
	v_add_f32_dpp v39, v41, v41 quad_perm:[2,3,0,1] row_mask:0xf bank_mask:0xf bound_ctrl:1
	v_add_f32_dpp v38, v38, v38 row_ror:4 row_mask:0xf bank_mask:0xf bound_ctrl:1
	v_rcp_f32_e32 v26, v4
	v_add_f32_dpp v39, v39, v39 row_ror:4 row_mask:0xf bank_mask:0xf bound_ctrl:1
	v_add_f32_dpp v38, v38, v38 row_ror:8 row_mask:0xf bank_mask:0xf bound_ctrl:1
	v_lshl_add_u64 v[4:5], v[92:93], 0, s[28:29]
	v_readlane_b32 s30, v38, 16
	v_readlane_b32 s31, v38, 48
	v_add_f32_dpp v41, v39, v39 row_ror:8 row_mask:0xf bank_mask:0xf bound_ctrl:1
	v_readlane_b32 s28, v38, 0
	v_readlane_b32 s29, v38, 32
	v_mov_b32_e32 v38, s30
	v_mov_b32_e32 v39, s31
	v_pk_add_f32 v[38:39], s[28:29], v[38:39]
	v_readlane_b32 s30, v41, 16
	v_readlane_b32 s31, v41, 48
	v_add_f32_e32 v44, v38, v39
	v_readlane_b32 s28, v41, 0
	v_readlane_b32 s29, v41, 32
	v_mov_b32_e32 v38, s30
	v_mov_b32_e32 v39, s31
	v_pk_add_f32 v[38:39], s[28:29], v[38:39]
	v_lshlrev_b32_e32 v41, 16, v140
	v_add_f32_e32 v39, v38, v39
	v_sqrt_f32_e32 v38, v44
	global_store_dword v[4:5], v41, off
	v_xor_b32_e32 v38, 0x80000000, v38
	v_min_f32_e32 v38, 0xab8cbccc, v38
	v_rcp_f32_e32 v38, v38
	s_nop 0
	v_mul_f32_e32 v38, v40, v38
	v_mov_b32_e32 v40, v224
	v_xor_b32_e32 v83, 0x80000000, v38
	v_pk_mul_f32 v[26:27], v[26:27], v[82:83]
	v_lshlrev_b32_e32 v40, 16, v40
	s_branch .LBB0_529

.LBB0_529:
	v_readlane_b32 s8, v250, 21
	s_nop 1
	v_add_u32_e32 v4, s8, v106
	ds_write_b32 v4, v26 offset:62464
	v_cvt_pk_bf16_f32 v4, v41, v2
	ds_write_b16 v42, v4 offset:144
	v_cvt_pk_bf16_f32 v4, v40, v2
	ds_write_b16 v43, v4 offset:144
	s_and_saveexec_b64 s[28:29], s[26:27]
	s_lshl_b32 s30, s73, 2
	s_add_i32 s30, s5, s30
	v_mov_b32_e32 v4, s30
	ds_write_b32 v4, v39 offset:8
	s_or_b64 exec, exec, s[28:29]
	s_add_i32 s4, s4, s89
	s_cmp_ge_i32 s4, s82
	s_cbranch_scc1 .LBB0_533
	v_mov_b32_e32 v4, v225
	v_mov_b32_e32 v5, v226
	v_mov_b32_e32 v46, v227
	v_lshlrev_b32_e32 v29, 16, v137
	v_mul_f32_e32 v41, v145, v29
	v_lshlrev_b32_e32 v39, 16, v136
	v_lshlrev_b32_e32 v3, 16, v4
	v_add_f32_e32 v3, v143, v3
	v_lshlrev_b32_e32 v4, 16, v5
	v_mul_f32_e32 v3, 0xbfb8aa3b, v3
	v_add_f32_e32 v4, v144, v4
	v_exp_f32_e32 v3, v3
	v_mul_f32_e32 v4, 0xbfb8aa3b, v4
	v_exp_f32_e32 v5, v4
	s_add_i32 s28, s4, s84
	v_add_f32_e32 v3, 1.0, v3
	v_rcp_f32_e32 v4, v3
	v_add_f32_e32 v3, 1.0, v5
	v_rcp_f32_e32 v5, v3
	s_ashr_i32 s29, s28, 31
	s_lshl_b64 s[28:29], s[28:29], 12
	v_lshl_add_u64 v[44:45], v[92:93], 0, s[28:29]
	v_add_f32_e32 v3, -1.0, v5
	v_fma_f32 v3, v146, v3, 1.0
	v_mul_f32_e32 v40, v3, v29
	v_mul_f32_e32 v3, v41, v41
	v_mul_f32_e32 v28, v40, v39
	v_mul_f32_e32 v29, v147, v28
	v_mov_b32_dpp v3, v3 quad_perm:[1,0,3,2] row_mask:0xf bank_mask:0xf bound_ctrl:1
	v_fmac_f32_e32 v3, v41, v41
	v_mov_b32_dpp v29, v29 quad_perm:[1,0,3,2] row_mask:0xf bank_mask:0xf bound_ctrl:1
	v_fmac_f32_e32 v29, v147, v28
	v_add_f32_dpp v3, v3, v3 quad_perm:[2,3,0,1] row_mask:0xf bank_mask:0xf bound_ctrl:1
	s_nop 0
	v_add_f32_dpp v28, v29, v29 quad_perm:[2,3,0,1] row_mask:0xf bank_mask:0xf bound_ctrl:1
	v_add_f32_dpp v3, v3, v3 row_ror:4 row_mask:0xf bank_mask:0xf bound_ctrl:1
	s_nop 0
	v_add_f32_dpp v28, v28, v28 row_ror:4 row_mask:0xf bank_mask:0xf bound_ctrl:1
	v_add_f32_dpp v3, v3, v3 row_ror:8 row_mask:0xf bank_mask:0xf bound_ctrl:1
	s_nop 0
	v_readlane_b32 s4, v3, 16
	v_readlane_b32 s30, v3, 48
	v_add_f32_dpp v47, v28, v28 row_ror:8 row_mask:0xf bank_mask:0xf bound_ctrl:1
	v_readlane_b32 s28, v3, 0
	v_readlane_b32 s29, v3, 32
	v_mov_b32_e32 v28, s4
	v_mov_b32_e32 v29, s30
	v_pk_add_f32 v[28:29], s[28:29], v[28:29]
	v_readlane_b32 s28, v47, 0
	v_add_f32_e32 v3, v28, v29
	v_sqrt_f32_e32 v3, v3
	v_readlane_b32 s4, v47, 16
	v_readlane_b32 s29, v47, 32
	v_readlane_b32 s30, v47, 48
	v_xor_b32_e32 v3, 0x80000000, v3
	v_min_f32_e32 v3, 0xab8cbccc, v3
	v_rcp_f32_e32 v47, v3
	v_mov_b32_e32 v28, s4
	v_mov_b32_e32 v29, s30
	v_pk_add_f32 v[28:29], s[28:29], v[28:29]
	v_mul_f32_e32 v41, v41, v47
	v_xor_b32_e32 v83, 0x80000000, v41
	v_add_f32_e32 v3, v28, v29
	v_pk_mul_f32 v[28:29], v[4:5], v[82:83]
	v_lshlrev_b32_e32 v4, 16, v46
	v_lshlrev_b32_e32 v5, 16, v141
	global_store_dword v[44:45], v5, off
	s_branch .LBB0_534

.LBB0_542:
	s_andn2_b64 vcc, exec, s[34:35]
	s_cbranch_vccnz .LBB0_580
	v_readlane_b32 s5, v250, 0
	s_mov_b64 s[34:35], -1
	s_and_b64 vcc, exec, s[6:7]
	v_add3_u32 v38, s5, v5, v4
	s_nop 5
	ds_read_b128 v[22:25], v38
	v_readlane_b32 s5, v250, 2
	s_nop 1
	v_add3_u32 v4, s5, v5, v4
	ds_read_b128 v[26:29], v4
	ds_read_b128 v[40:43], v38 offset:32
	ds_read_b128 v[44:47], v4 offset:32
	ds_read_b128 v[176:179], v38 offset:64
	ds_read_b128 v[180:183], v4 offset:64
	ds_read_b128 v[184:187], v38 offset:96
	ds_read_b128 v[188:191], v4 offset:96
	s_waitcnt lgkmcnt(6)
	v_mfma_f32_32x32x16_bf16 v[22:37], v[22:25], v[26:29], 0
	v_readlane_b32 s5, v250, 8
	v_lshlrev_b32_e32 v5, 2, v39
	s_waitcnt lgkmcnt(4)
	v_mfma_f32_32x32x16_bf16 v[22:37], v[40:43], v[44:47], v[22:37]
	s_waitcnt lgkmcnt(2)
	v_mfma_f32_32x32x16_bf16 v[22:37], v[176:179], v[180:183], v[22:37]
	v_lshl_add_u32 v4, v3, 1, s5
	s_waitcnt lgkmcnt(0)
	v_mfma_f32_32x32x16_bf16 v[22:37], v[184:187], v[188:191], v[22:37]
	s_cbranch_vccz .Lst3_nab_2
	v_cndmask_b32_e64 v38, 1, 0, s[96:97]
	v_sub_u32_e32 v40, v3, v5
	v_lshl_add_u32 v208, v39, 8, v4
	v_sub_u32_e32 v209, v40, v38
	v_lshl_add_u32 v208, v39, 6, v208
	s_nop 7
	s_nop 3
	v_cmp_gt_i32_e64 vcc, 0, v209
	v_cmp_gt_i32_e64 s[34:35], 1, v209
	v_cmp_gt_i32_e64 s[92:93], 2, v209
	v_cndmask_b32_e64 v38, 0, v22, vcc
	v_cvt_pk_bf16_f32 v38, v38, v2
	ds_write_b16 v208, v38
	v_cmp_gt_i32_e64 vcc, 3, v209
	v_cndmask_b32_e64 v40, 0, v23, s[34:35]
	v_cvt_pk_bf16_f32 v40, v40, v2
	ds_write_b16 v208, v40 offset:80
	v_cmp_gt_i32_e64 s[34:35], 8, v209
	v_cndmask_b32_e64 v41, 0, v24, s[92:93]
	v_cvt_pk_bf16_f32 v41, v41, v2
	ds_write_b16 v208, v41 offset:160
	v_cmp_gt_i32_e64 s[92:93], 9, v209
	v_cndmask_b32_e64 v42, 0, v25, vcc
	v_cvt_pk_bf16_f32 v42, v42, v2
	ds_write_b16 v208, v42 offset:240
	v_cmp_gt_i32_e64 vcc, 10, v209
	v_cndmask_b32_e64 v38, 0, v26, s[34:35]
	v_cvt_pk_bf16_f32 v38, v38, v2
	ds_write_b16 v208, v38 offset:640
	v_cmp_gt_i32_e64 s[34:35], 11, v209
	v_cndmask_b32_e64 v40, 0, v27, s[92:93]
	v_cvt_pk_bf16_f32 v40, v40, v2
	ds_write_b16 v208, v40 offset:720
	v_cmp_gt_i32_e64 s[92:93], 16, v209
	v_cndmask_b32_e64 v41, 0, v28, vcc
	v_cvt_pk_bf16_f32 v41, v41, v2
	ds_write_b16 v208, v41 offset:800
	v_cmp_gt_i32_e64 vcc, 17, v209
	v_cndmask_b32_e64 v42, 0, v29, s[34:35]
	v_cvt_pk_bf16_f32 v42, v42, v2
	ds_write_b16 v208, v42 offset:880
	v_cmp_gt_i32_e64 s[34:35], 18, v209
	v_cndmask_b32_e64 v38, 0, v30, s[92:93]
	v_cvt_pk_bf16_f32 v38, v38, v2
	ds_write_b16 v208, v38 offset:1280
	v_cmp_gt_i32_e64 s[92:93], 19, v209
	v_cndmask_b32_e64 v40, 0, v31, vcc
	v_cvt_pk_bf16_f32 v40, v40, v2
	ds_write_b16 v208, v40 offset:1360
	v_cmp_gt_i32_e64 vcc, 24, v209
	v_cndmask_b32_e64 v41, 0, v32, s[34:35]
	v_cvt_pk_bf16_f32 v41, v41, v2
	ds_write_b16 v208, v41 offset:1440
	v_cmp_gt_i32_e64 s[34:35], 25, v209
	v_cndmask_b32_e64 v42, 0, v33, s[92:93]
	v_cvt_pk_bf16_f32 v42, v42, v2
	ds_write_b16 v208, v42 offset:1520
	v_cmp_gt_i32_e64 s[92:93], 26, v209
	v_cndmask_b32_e64 v38, 0, v34, vcc
	v_cvt_pk_bf16_f32 v38, v38, v2
	ds_write_b16 v208, v38 offset:1920
	v_cmp_gt_i32_e64 vcc, 27, v209
	v_cndmask_b32_e64 v40, 0, v35, s[34:35]
	v_cvt_pk_bf16_f32 v40, v40, v2
	ds_write_b16 v208, v40 offset:2000
	v_cndmask_b32_e64 v41, 0, v36, s[92:93]
	v_cvt_pk_bf16_f32 v41, v41, v2
	ds_write_b16 v208, v41 offset:2080
	v_cndmask_b32_e64 v42, 0, v37, vcc
	v_cvt_pk_bf16_f32 v42, v42, v2
	ds_write_b16 v208, v42 offset:2160
	s_branch .Lst3_join_2
.Lst3_nab_2:
	v_sub_u32_e32 v209, v3, v5
	v_lshlrev_b32_e32 v40, 2, v3
	v_lshl_add_u32 v208, v39, 9, v40
	s_nop 7
	s_nop 5
	v_cmp_lt_i32_e64 vcc, 0, v209
	v_cmp_lt_i32_e64 s[34:35], 1, v209
	v_cmp_lt_i32_e64 s[92:93], 2, v209
	v_cndmask_b32_e64 v38, 0, v22, vcc
	ds_write_b32 v208, v38 offset:58368
	v_cmp_lt_i32_e64 vcc, 3, v209
	v_cndmask_b32_e64 v40, 0, v23, s[34:35]
	ds_write_b32 v208, v40 offset:58496
	v_cmp_lt_i32_e64 s[34:35], 8, v209
	v_cndmask_b32_e64 v41, 0, v24, s[92:93]
	ds_write_b32 v208, v41 offset:58624
	v_cmp_lt_i32_e64 s[92:93], 9, v209
	v_cndmask_b32_e64 v42, 0, v25, vcc
	ds_write_b32 v208, v42 offset:58752
	v_cmp_lt_i32_e64 vcc, 10, v209
	v_cndmask_b32_e64 v38, 0, v26, s[34:35]
	ds_write_b32 v208, v38 offset:59392
	v_cmp_lt_i32_e64 s[34:35], 11, v209
	v_cndmask_b32_e64 v40, 0, v27, s[92:93]
	ds_write_b32 v208, v40 offset:59520
	v_cmp_lt_i32_e64 s[92:93], 16, v209
	v_cndmask_b32_e64 v41, 0, v28, vcc
	ds_write_b32 v208, v41 offset:59648
	v_cmp_lt_i32_e64 vcc, 17, v209
	v_cndmask_b32_e64 v42, 0, v29, s[34:35]
	ds_write_b32 v208, v42 offset:59776
	v_cmp_lt_i32_e64 s[34:35], 18, v209
	v_cndmask_b32_e64 v38, 0, v30, s[92:93]
	ds_write_b32 v208, v38 offset:60416
	v_cmp_lt_i32_e64 s[92:93], 19, v209
	v_cndmask_b32_e64 v40, 0, v31, vcc
	ds_write_b32 v208, v40 offset:60544
	v_cmp_lt_i32_e64 vcc, 24, v209
	v_cndmask_b32_e64 v41, 0, v32, s[34:35]
	ds_write_b32 v208, v41 offset:60672
	v_cmp_lt_i32_e64 s[34:35], 25, v209
	v_cndmask_b32_e64 v42, 0, v33, s[92:93]
	ds_write_b32 v208, v42 offset:60800
	v_cmp_lt_i32_e64 s[92:93], 26, v209
	v_cndmask_b32_e64 v38, 0, v34, vcc
	ds_write_b32 v208, v38 offset:61440
	v_cmp_lt_i32_e64 vcc, 27, v209
	v_cndmask_b32_e64 v40, 0, v35, s[34:35]
	ds_write_b32 v208, v40 offset:61568
	v_cndmask_b32_e64 v41, 0, v36, s[92:93]
	ds_write_b32 v208, v41 offset:61696
	v_cndmask_b32_e64 v42, 0, v37, vcc
	ds_write_b32 v208, v42 offset:61824
.Lst3_join_2:
	s_movk_i32 s93, 0x90
.LBB0_580:
	v_readlane_b32 s8, v250, 10
	v_readlane_b32 s9, v250, 11
	s_andn2_b64 vcc, exec, s[8:9]
	s_waitcnt lgkmcnt(0)
	s_barrier
	s_cbranch_vccnz .LBB0_582
	v_mov_b32_e32 v3, v71
	s_add_i32 s5, s90, 0
	v_and_b32_e32 v4, 31, v3
	v_ashrrev_i32_e32 v5, 5, v3
	v_mul_u32_u24_e32 v38, 0x50, v4
	v_lshlrev_b32_e32 v39, 4, v5
	v_add3_u32 v46, 0, v38, v39
	v_lshrrev_b32_e32 v38, 2, v3
	v_and_b32_e32 v39, 16, v3
	v_lshlrev_b32_e32 v3, 2, v3
	v_and_b32_e32 v38, 0xffffffb, v38
	v_and_b32_e32 v3, 12, v3
	v_or3_b32 v3, v39, v3, s72
	v_mul_lo_u32 v44, v38, s93
	ds_read_b128 v[38:41], v46 offset:50688
	v_lshlrev_b32_e32 v3, 1, v3
	v_add3_u32 v47, s5, v3, v44
	v_add3_u32 v3, s5, v44, v3
	ds_read_b64_tr_b16 v[42:43], v47
	ds_read_b64_tr_b16 v[44:45], v3 offset:576
	ds_read_b128 v[208:211], v46 offset:50720
	ds_read_b64_tr_b16 v[212:213], v47 offset:2304
	ds_read_b64_tr_b16 v[214:215], v3 offset:2880
	s_waitcnt lgkmcnt(3)
	v_mfma_f32_32x32x16_bf16 v[22:37], v[38:41], v[42:45], v[22:37]
	v_lshlrev_b32_e32 v3, 10, v5
	v_lshlrev_b32_e32 v4, 2, v4
	v_readlane_b32 s5, v250, 12
	s_nop 1
	v_add3_u32 v3, s5, v3, v4
	s_waitcnt lgkmcnt(0)
	v_mfma_f32_32x32x16_bf16 v[22:37], v[208:211], v[212:215], v[22:37]
	v_add_u32_e32 v4, 0xf400, v3
	s_nop 10
	ds_write2st64_b32 v3, v22, v23 offset0:244 offset1:245
	ds_write2st64_b32 v3, v24, v25 offset0:246 offset1:247
	ds_write2st64_b32 v3, v26, v27 offset0:252 offset1:253
	ds_write2st64_b32 v3, v28, v29 offset0:254 offset1:255
	ds_write2st64_b32 v4, v30, v31 offset0:16 offset1:17
	ds_write2st64_b32 v4, v32, v33 offset0:18 offset1:19
	ds_write2st64_b32 v4, v34, v35 offset0:24 offset1:25
	ds_write2st64_b32 v4, v36, v37 offset0:26 offset1:27

.LBB0_587:
	v_readlane_b32 s8, v250, 14
	v_mov_b32_e32 v4, v71
	v_readlane_b32 s9, v250, 15
	s_waitcnt lgkmcnt(0)
	s_barrier
	s_mov_b64 s[30:31], -1
	v_and_b32_e32 v3, 31, v4
	s_and_b64 vcc, exec, s[8:9]
	s_cbranch_vccz .LBB0_591
	v_mov_b64_e32 v[52:53], v[20:21]
	s_and_b64 vcc, exec, s[28:29]
	v_mov_b64_e32 v[50:51], v[18:19]
	v_mov_b64_e32 v[48:49], v[16:17]
	v_mov_b64_e32 v[46:47], v[14:15]
	v_mov_b64_e32 v[44:45], v[12:13]
	v_mov_b64_e32 v[42:43], v[10:11]
	v_mov_b64_e32 v[40:41], v[8:9]
	v_mov_b64_e32 v[38:39], v[6:7]
	s_cbranch_vccnz .LBB0_590
	v_readlane_b32 s5, v250, 16
	v_and_b32_e32 v83, 16, v4
	v_lshlrev_b32_e32 v85, 2, v4
	v_lshl_add_u32 v5, v3, 2, s5
	ds_read_b32 v38, v5
	v_lshrrev_b32_e32 v5, 2, v4
	v_and_or_b32 v83, v85, 12, v83
	v_readlane_b32 s5, v253, 62
	v_and_b32_e32 v5, 0xffffffb, v5
	v_mul_lo_u32 v5, v5, s93
	v_or_b32_e32 v85, s5, v83
	v_or_b32_e32 v83, s72, v83
	v_lshlrev_b32_e32 v85, 1, v85
	v_lshlrev_b32_e32 v83, 1, v83
	v_add3_u32 v86, 0, v85, v5
	v_add3_u32 v83, 0, v83, v5
	ds_read_b64_tr_b16 v[94:95], v86 offset:32256
	ds_read_b64_tr_b16 v[96:97], v86 offset:32832
	ds_read_b64_tr_b16 v[98:99], v83 offset:18432
	ds_read_b64_tr_b16 v[100:101], v83 offset:19008
	s_add_i32 s5, s90, 0
	v_add3_u32 v5, s5, v85, v5
	ds_read_b64_tr_b16 v[208:209], v5
	ds_read_b64_tr_b16 v[210:211], v5 offset:576
	ds_read_b64_tr_b16 v[212:213], v83 offset:23040
	ds_read_b64_tr_b16 v[214:215], v83 offset:23616
	ds_read_b64_tr_b16 v[216:217], v86 offset:34560
	ds_read_b64_tr_b16 v[218:219], v86 offset:35136
	ds_read_b64_tr_b16 v[220:221], v83 offset:20736
	ds_read_b64_tr_b16 v[222:223], v83 offset:21312
	s_waitcnt lgkmcnt(12)
	v_pk_mul_f32 v[52:53], v[20:21], v[38:39] op_sel_hi:[1,0]
	v_pk_mul_f32 v[50:51], v[18:19], v[38:39] op_sel_hi:[1,0]
	v_pk_mul_f32 v[48:49], v[16:17], v[38:39] op_sel_hi:[1,0]
	v_pk_mul_f32 v[46:47], v[14:15], v[38:39] op_sel_hi:[1,0]
	v_pk_mul_f32 v[44:45], v[12:13], v[38:39] op_sel_hi:[1,0]
	v_pk_mul_f32 v[42:43], v[10:11], v[38:39] op_sel_hi:[1,0]
	v_pk_mul_f32 v[40:41], v[8:9], v[38:39] op_sel_hi:[1,0]
	v_pk_mul_f32 v[38:39], v[6:7], v[38:39] op_sel_hi:[1,0]
	s_waitcnt lgkmcnt(8)
	ds_read_b64_tr_b16 v[224:225], v5 offset:2304
	ds_read_b64_tr_b16 v[226:227], v5 offset:2880
	ds_read_b64_tr_b16 v[228:229], v83 offset:25344
	ds_read_b64_tr_b16 v[230:231], v83 offset:25920
	v_mfma_f32_32x32x16_bf16 v[38:53], v[94:97], v[98:101], v[38:53]
	s_waitcnt lgkmcnt(8)
	v_mfma_f32_32x32x16_bf16 v[38:53], v[208:211], v[212:215], v[38:53]
	s_waitcnt lgkmcnt(4)
	v_mfma_f32_32x32x16_bf16 v[38:53], v[216:219], v[220:223], v[38:53]
	s_waitcnt lgkmcnt(0)
	v_mfma_f32_32x32x16_bf16 v[38:53], v[224:227], v[228:231], v[38:53]

.LBB0_591:
	s_andn2_b64 vcc, exec, s[30:31]
	s_cbranch_vccnz .LBB0_593
	v_ashrrev_i32_e32 v5, 5, v4
	s_nop 7
	v_lshrrev_b32_e32 v40, 2, v4
	v_and_b32_e32 v41, 16, v4
	v_lshlrev_b32_e32 v4, 2, v4
	v_and_b32_e32 v4, 12, v4
	v_and_b32_e32 v40, 0xffffffb, v40
	v_or3_b32 v4, v41, v4, s72
	v_lshlrev_b32_e32 v4, 1, v4
	v_mul_lo_u32 v51, v40, s93
	v_mul_u32_u24_e32 v38, 0x50, v3
	v_lshlrev_b32_e32 v39, 4, v5
	v_add3_u32 v52, 0, v4, v51
	v_add3_u32 v50, 0, v38, v39
	ds_read_b64_tr_b16 v[38:39], v52 offset:32256
	ds_read_b64_tr_b16 v[40:41], v52 offset:32832
	ds_read_b128 v[42:45], v50 offset:53248
	ds_read_b128 v[46:49], v50 offset:53280
	s_add_i32 s5, s90, 0
	v_add3_u32 v4, s5, v4, v51
	ds_read_b128 v[208:211], v50 offset:55808
	ds_read_b64_tr_b16 v[212:213], v4
	ds_read_b64_tr_b16 v[214:215], v4 offset:576
	ds_read_b64_tr_b16 v[216:217], v52 offset:34560
	ds_read_b64_tr_b16 v[218:219], v52 offset:35136
	ds_read_b128 v[220:223], v50 offset:55840
	ds_read_b64_tr_b16 v[224:225], v4 offset:2304
	ds_read_b64_tr_b16 v[226:227], v4 offset:2880
	v_lshlrev_b32_e32 v3, 2, v3
	v_readlane_b32 s5, v250, 17
	s_waitcnt lgkmcnt(9)
	v_mfma_f32_32x32x16_bf16 v[22:37], v[42:45], v[38:41], v[22:37]
	s_waitcnt lgkmcnt(5)
	v_mfma_f32_32x32x16_bf16 v[22:37], v[208:211], v[212:215], v[22:37]
	s_waitcnt lgkmcnt(3)
	v_mfma_f32_32x32x16_bf16 v[22:37], v[46:49], v[216:219], v[22:37]
	v_lshlrev_b32_e32 v4, 10, v5
	v_add3_u32 v3, s5, v4, v3
	s_waitcnt lgkmcnt(0)
	v_mfma_f32_32x32x16_bf16 v[22:37], v[220:223], v[224:227], v[22:37]
	v_mov_b64_e32 v[52:53], v[20:21]
	v_mov_b64_e32 v[50:51], v[18:19]
	v_mov_b64_e32 v[48:49], v[16:17]
	v_mov_b64_e32 v[46:47], v[14:15]
	v_mov_b64_e32 v[44:45], v[12:13]
	v_mov_b64_e32 v[42:43], v[10:11]
	v_mov_b64_e32 v[40:41], v[8:9]
	v_mov_b64_e32 v[38:39], v[6:7]
	s_nop 3
	ds_write2st64_b32 v3, v22, v23 offset1:1
	ds_write2st64_b32 v3, v24, v25 offset0:2 offset1:3
	ds_write2st64_b32 v3, v26, v27 offset0:8 offset1:9
	ds_write2st64_b32 v3, v28, v29 offset0:10 offset1:11
	ds_write2st64_b32 v3, v30, v31 offset0:16 offset1:17
	ds_write2st64_b32 v3, v32, v33 offset0:18 offset1:19
	ds_write2st64_b32 v3, v34, v35 offset0:24 offset1:25
	ds_write2st64_b32 v3, v36, v37 offset0:26 offset1:27

.LBB0_607:
	s_or_b64 exec, exec, s[28:29]
	v_cndmask_b32_e64 v3, 0, 1, s[0:1]
	v_cmp_ne_u32_e64 s[28:29], 1, v3
	s_andn2_b64 vcc, exec, s[0:1]
	s_cbranch_vccz .LBB0_537
	s_branch .LBB0_538
.LBB0_635:
	s_add_i32 s29, s28, s84
	v_mad_i64_i32 v[4:5], s[30:31], s29, v129, v[90:91]
	global_load_ushort v130, v[4:5], off
	global_load_ushort v131, v[4:5], off offset:2048
	v_add_co_u32_e32 v4, vcc, 0x1000, v4
	s_nop 1
	v_addc_co_u32_e32 v5, vcc, 0, v5, vcc
	global_load_ushort v138, v[4:5], off
	s_or_b32 s29, s28, 1
	s_cmp_ge_i32 s29, s82
	s_cbranch_scc1 .LBB0_598

.Lrs0_done_3305:
	s_nop 3
	s_movk_i32 s24, 0x240
	v_lshlrev_b32_e32 v4, 1, v4
	v_mul_lo_u32 v3, v3, s24
	v_add3_u32 v3, s88, v4, v3
	v_cvt_pk_bf16_f32 v4, v22, v2
	ds_write_b16 v3, v4
	v_cvt_pk_bf16_f32 v4, v23, v2
	ds_write_b16 v3, v4 offset:144
	v_cvt_pk_bf16_f32 v4, v24, v2
	ds_write_b16 v3, v4 offset:288
	v_cvt_pk_bf16_f32 v4, v25, v2
	ds_write_b16 v3, v4 offset:432
	v_cvt_pk_bf16_f32 v4, v26, v2
	ds_write_b16 v3, v4 offset:1152
	v_cvt_pk_bf16_f32 v4, v27, v2
	ds_write_b16 v3, v4 offset:1296
	v_cvt_pk_bf16_f32 v4, v28, v2
	ds_write_b16 v3, v4 offset:1440
	v_cvt_pk_bf16_f32 v4, v29, v2
	ds_write_b16 v3, v4 offset:1584
	v_cvt_pk_bf16_f32 v4, v30, v2
	ds_write_b16 v3, v4 offset:2304
	v_cvt_pk_bf16_f32 v4, v31, v2
	ds_write_b16 v3, v4 offset:2448
	v_cvt_pk_bf16_f32 v4, v32, v2
	ds_write_b16 v3, v4 offset:2592
	v_cvt_pk_bf16_f32 v4, v33, v2
	ds_write_b16 v3, v4 offset:2736
	v_cvt_pk_bf16_f32 v4, v34, v2
	ds_write_b16 v3, v4 offset:3456
	v_cvt_pk_bf16_f32 v4, v35, v2
	s_lshl_b32 s23, s25, 5
	ds_write_b16 v3, v4 offset:3600
	v_cvt_pk_bf16_f32 v4, v36, v2
	ds_write_b16 v3, v4 offset:3744
	v_cvt_pk_bf16_f32 v4, v37, v2
	s_sub_i32 s24, s57, s23
	ds_write_b16 v3, v4 offset:3888
	v_mov_b32_e32 v31, 0
	s_cmp_lt_i32 s55, s24
	v_mov_b32_e32 v30, 0
	v_mov_b32_e32 v4, 0
	v_mov_b32_e32 v5, 0
	v_mov_b32_e32 v22, 0
	v_mov_b32_e32 v23, 0
	v_mov_b32_e32 v3, 0
	v_mov_b32_e32 v32, 0
	s_waitcnt lgkmcnt(0)
	s_barrier
	v_add_u32_e32 v208, s90, v107
	v_add_u32_e32 v209, s90, v108
	v_add_u32_e32 v210, s90, v109
	v_add_u32_e32 v211, s90, v110
	v_add_u32_e32 v212, s91, v107
	v_add_u32_e32 v213, s91, v108
	v_add_u32_e32 v214, s91, v109
	v_add_u32_e32 v215, s91, v110
	ds_read_u16 v216, v208
	ds_read_u16 v217, v209
	ds_read_u16 v218, v210
	ds_read_u16 v219, v211
	ds_read_u16 v220, v212
	ds_read_u16 v221, v213
	ds_read_u16 v222, v214
	ds_read_u16 v223, v215
	ds_read_u16 v224, v212 offset:144
	ds_read_u16 v225, v213 offset:144
	ds_read_u16 v226, v214 offset:144
	ds_read_u16 v227, v215 offset:144
	ds_read_u16 v228, v212 offset:288
	ds_read_u16 v229, v213 offset:288
	ds_read_u16 v230, v214 offset:288
	ds_read_u16 v231, v215 offset:288
	s_waitcnt lgkmcnt(0)
	s_cbranch_scc0 .LBB0_3308
	v_add_u32_e32 v5, s90, v107
	v_add_u32_e32 v22, s90, v108
	v_add_u32_e32 v23, s90, v109
	v_mov_b32_e32 v5, v216
	v_add_u32_e32 v24, s90, v110
	v_mov_b32_e32 v22, v217
	v_mov_b32_e32 v23, v218
	v_mov_b32_e32 v26, v219
	v_lshlrev_b32_e32 v3, 16, v133
	v_mul_f32_e32 v28, v150, v3
	v_lshlrev_b32_e32 v22, 16, v22
	v_add_f32_e32 v22, v153, v22
	v_mul_f32_e32 v22, 0xbfb8aa3b, v22
	v_exp_f32_e32 v24, v22
	v_lshlrev_b32_e32 v5, 16, v5
	v_add_f32_e32 v5, v148, v5
	v_mul_f32_e32 v5, 0xbfb8aa3b, v5
	v_add_f32_e32 v24, 1.0, v24
	v_rcp_f32_e32 v27, v24
	v_mul_f32_e32 v24, v28, v28
	v_lshlrev_b32_e32 v23, 16, v23
	v_exp_f32_e32 v5, v5
	v_mov_b32_dpp v24, v24 quad_perm:[1,0,3,2] row_mask:0xf bank_mask:0xf bound_ctrl:1
	v_fmac_f32_e32 v24, v28, v28
	v_add_f32_e32 v23, v149, v23
	v_mul_f32_e32 v23, 0xbfb8aa3b, v23
	v_add_f32_dpp v24, v24, v24 quad_perm:[2,3,0,1] row_mask:0xf bank_mask:0xf bound_ctrl:1
	v_exp_f32_e32 v23, v23
	v_lshlrev_b32_e32 v4, 16, v137
	v_add_f32_dpp v24, v24, v24 row_ror:4 row_mask:0xf bank_mask:0xf bound_ctrl:1
	v_add_f32_e32 v5, 1.0, v5
	v_rcp_f32_e32 v22, v5
	v_add_f32_dpp v24, v24, v24 row_ror:8 row_mask:0xf bank_mask:0xf bound_ctrl:1
	v_sub_f32_e32 v5, v142, v4
	v_readlane_b32 s23, v24, 16
	v_readlane_b32 s30, v24, 48
	v_readlane_b32 s28, v24, 0
	v_readlane_b32 s29, v24, 32
	v_mov_b32_e32 v24, s23
	v_mov_b32_e32 v25, s30
	v_pk_add_f32 v[24:25], s[28:29], v[24:25]
	v_lshlrev_b32_e32 v32, 16, v132
	v_add_f32_e32 v24, v24, v25
	v_sqrt_f32_e32 v25, v24
	v_mul_f32_e32 v24, v5, v27
	v_add_f32_e32 v5, 1.0, v23
	v_rcp_f32_e32 v23, v5
	v_xor_b32_e32 v5, 0x80000000, v25
	v_min_f32_e32 v5, 0xab8cbccc, v5
	v_rcp_f32_e32 v5, v5
	v_add_f32_e32 v25, -1.0, v23
	v_fma_f32 v25, v151, v25, 1.0
	v_mul_f32_e32 v30, v25, v3
	v_mul_f32_e32 v31, v28, v5
	v_mul_f32_e32 v5, v30, v32
	v_mul_f32_e32 v25, v152, v5
	v_xor_b32_e32 v83, 0x80000000, v31
	v_pk_mul_f32 v[22:23], v[22:23], v[82:83]
	v_mov_b32_dpp v25, v25 quad_perm:[1,0,3,2] row_mask:0xf bank_mask:0xf bound_ctrl:1
	v_fmac_f32_e32 v25, v152, v5
	v_lshlrev_b32_e32 v3, 16, v26
	v_add_f32_dpp v5, v25, v25 quad_perm:[2,3,0,1] row_mask:0xf bank_mask:0xf bound_ctrl:1
	s_nop 1
	v_add_f32_dpp v5, v5, v5 row_ror:4 row_mask:0xf bank_mask:0xf bound_ctrl:1
	s_nop 1
	v_add_f32_dpp v5, v5, v5 row_ror:8 row_mask:0xf bank_mask:0xf bound_ctrl:1
	s_nop 0
	v_readlane_b32 s28, v5, 16
	v_readlane_b32 s23, v5, 0
	s_nop 0
	v_mov_b32_e32 v25, s28
	v_readlane_b32 s28, v5, 48
	v_add_f32_e32 v25, s23, v25
	v_readlane_b32 s23, v5, 32
	v_mov_b32_e32 v5, s28
	s_nop 0
	v_add_f32_e32 v5, s23, v5
	v_pk_add_f32 v[4:5], v[24:25], v[4:5]
.LBB0_3308:
	s_and_b32 s28, s25, 1
	s_cmp_eq_u32 s28, 0
	s_movk_i32 s23, 0x6c00
	s_cselect_b32 s23, s23, 0x13600
	s_cselect_b32 s29, s20, 0x14800
	v_add_u32_e32 v27, s23, v113
	s_lshl_b32 s28, s28, 7
	v_add_u32_e32 v24, s46, v111
	v_add_u32_e32 v26, s29, v113
	s_add_i32 s30, s28, 0
	ds_write_b32 v24, v22 offset:62464
	v_add_u32_e32 v24, s90, v27
	v_cvt_pk_bf16_f32 v4, v4, v2
	s_add_i32 s30, s30, 0x13500
	ds_write_b16 v24, v4
	v_add_u32_e32 v4, s90, v26
	v_cvt_pk_bf16_f32 v3, v3, v2
	ds_write_b16 v4, v3
	s_and_saveexec_b64 s[28:29], s[26:27]
	s_lshl_b32 s31, s55, 2
	s_add_i32 s31, s30, s31
	v_mov_b32_e32 v3, s31
	ds_write_b32 v3, v5
	s_or_b64 exec, exec, s[28:29]
	v_mov_b32_e32 v34, 0
	s_cmp_ge_i32 s52, s24
	v_add_u32_e32 v44, s91, v107
	v_add_u32_e32 v43, s91, v108
	v_add_u32_e32 v42, s91, v109
	v_add_u32_e32 v3, s91, v110
	v_mov_b32_e32 v33, 0
	v_mov_b32_e32 v4, 0
	v_mov_b32_e32 v5, 0
	v_mov_b32_e32 v24, 0
	v_mov_b32_e32 v25, 0
	v_mov_b32_e32 v28, 0
	v_mov_b32_e32 v35, 0
	s_cbranch_scc1 .LBB0_3312
	v_mov_b32_e32 v24, v220
	v_mov_b32_e32 v25, v221
	v_mov_b32_e32 v28, v222
	v_mov_b32_e32 v35, v223
	v_lshlrev_b32_e32 v5, 16, v135
	v_mul_f32_e32 v37, v150, v5
	v_lshlrev_b32_e32 v25, 16, v25
	v_lshlrev_b32_e32 v28, 16, v28
	v_add_f32_e32 v28, v149, v28
	v_mul_f32_e32 v28, 0xbfb8aa3b, v28
	v_exp_f32_e32 v34, v28
	v_mul_f32_e32 v28, v37, v37
	v_add_f32_e32 v25, v153, v25
	v_mul_f32_e32 v25, 0xbfb8aa3b, v25
	v_mov_b32_dpp v28, v28 quad_perm:[1,0,3,2] row_mask:0xf bank_mask:0xf bound_ctrl:1
	v_fmac_f32_e32 v28, v37, v37
	v_exp_f32_e32 v25, v25
	v_lshlrev_b32_e32 v4, 16, v140
	v_add_f32_dpp v28, v28, v28 quad_perm:[2,3,0,1] row_mask:0xf bank_mask:0xf bound_ctrl:1
	v_sub_f32_e32 v33, v144, v4
	v_add_f32_e32 v25, 1.0, v25
	v_add_f32_dpp v28, v28, v28 row_ror:4 row_mask:0xf bank_mask:0xf bound_ctrl:1
	v_rcp_f32_e32 v25, v25
	v_lshlrev_b32_e32 v24, 16, v24
	v_add_f32_dpp v28, v28, v28 row_ror:8 row_mask:0xf bank_mask:0xf bound_ctrl:1
	v_add_f32_e32 v24, v148, v24
	v_readlane_b32 s31, v28, 16
	v_readlane_b32 s34, v28, 48
	v_readlane_b32 s28, v28, 0
	v_readlane_b32 s29, v28, 32
	v_mov_b32_e32 v28, s31
	v_mov_b32_e32 v29, s34
	v_pk_add_f32 v[28:29], s[28:29], v[28:29]
	v_mul_f32_e32 v36, v33, v25
	v_add_f32_e32 v28, v28, v29
	v_sqrt_f32_e32 v28, v28
	v_add_f32_e32 v25, 1.0, v34
	v_rcp_f32_e32 v25, v25
	v_mul_f32_e32 v24, 0xbfb8aa3b, v24
	v_xor_b32_e32 v28, 0x80000000, v28
	v_min_f32_e32 v28, 0xab8cbccc, v28
	v_rcp_f32_e32 v28, v28
	v_add_f32_e32 v29, -1.0, v25
	v_fma_f32 v29, v151, v29, 1.0
	v_mul_f32_e32 v33, v29, v5
	v_mul_f32_e32 v34, v37, v28
	v_lshlrev_b32_e32 v28, 16, v35
	v_lshlrev_b32_e32 v35, 16, v134
	v_mul_f32_e32 v5, v33, v35
	v_mul_f32_e32 v29, v152, v5
	v_exp_f32_e32 v24, v24
	v_xor_b32_e32 v83, 0x80000000, v34
	v_mov_b32_dpp v29, v29 quad_perm:[1,0,3,2] row_mask:0xf bank_mask:0xf bound_ctrl:1
	v_fmac_f32_e32 v29, v152, v5
	v_add_f32_e32 v24, 1.0, v24
	v_rcp_f32_e32 v24, v24
	v_add_f32_dpp v5, v29, v29 quad_perm:[2,3,0,1] row_mask:0xf bank_mask:0xf bound_ctrl:1
	v_pk_mul_f32 v[24:25], v[24:25], v[82:83]
	s_nop 0
	v_add_f32_dpp v5, v5, v5 row_ror:4 row_mask:0xf bank_mask:0xf bound_ctrl:1
	s_nop 1
	v_add_f32_dpp v5, v5, v5 row_ror:8 row_mask:0xf bank_mask:0xf bound_ctrl:1
	s_nop 0
	v_readlane_b32 s29, v5, 16
	v_readlane_b32 s28, v5, 0
	s_nop 0
	v_mov_b32_e32 v29, s29
	v_readlane_b32 s29, v5, 48
	v_add_f32_e32 v37, s28, v29
	v_readlane_b32 s28, v5, 32
	v_mov_b32_e32 v5, s29
	s_nop 0
	v_add_f32_e32 v5, s28, v5
	v_pk_add_f32 v[4:5], v[36:37], v[4:5]
.LBB0_3312:
	v_add_u32_e32 v29, s94, v111
	ds_write_b32 v29, v24 offset:62464
	v_add_u32_e32 v45, s91, v27
	v_cvt_pk_bf16_f32 v4, v4, v2
	v_add_u32_e32 v46, s91, v26
	ds_write_b16 v45, v4
	v_cvt_pk_bf16_f32 v4, v28, v2
	ds_write_b16 v46, v4
	s_and_saveexec_b64 s[28:29], s[26:27]
	s_lshl_b32 s31, s55, 2
	s_add_i32 s31, s30, s31
	v_mov_b32_e32 v4, s31
	ds_write_b32 v4, v5 offset:4
	s_or_b64 exec, exec, s[28:29]
	v_mov_b32_e32 v37, 0
	s_cmp_ge_i32 s56, s24
	v_mov_b32_e32 v36, 0
	v_mov_b32_e32 v4, 0
	v_mov_b32_e32 v5, 0
	v_mov_b32_e32 v26, 0
	v_mov_b32_e32 v27, 0
	v_mov_b32_e32 v28, 0
	v_mov_b32_e32 v38, 0
	s_cbranch_scc1 .LBB0_3316
	v_mov_b32_e32 v26, v224
	v_mov_b32_e32 v27, v225
	v_mov_b32_e32 v28, v226
	v_mov_b32_e32 v38, v227
	v_lshlrev_b32_e32 v5, 16, v138
	v_mul_f32_e32 v39, v150, v5
	v_lshlrev_b32_e32 v27, 16, v27
	v_lshlrev_b32_e32 v28, 16, v28
	v_add_f32_e32 v28, v149, v28
	v_mul_f32_e32 v28, 0xbfb8aa3b, v28
	v_exp_f32_e32 v37, v28
	v_mul_f32_e32 v28, v39, v39
	v_add_f32_e32 v27, v153, v27
	v_mul_f32_e32 v27, 0xbfb8aa3b, v27
	v_mov_b32_dpp v28, v28 quad_perm:[1,0,3,2] row_mask:0xf bank_mask:0xf bound_ctrl:1
	v_fmac_f32_e32 v28, v39, v39
	v_exp_f32_e32 v27, v27
	v_lshlrev_b32_e32 v4, 16, v143
	v_add_f32_dpp v28, v28, v28 quad_perm:[2,3,0,1] row_mask:0xf bank_mask:0xf bound_ctrl:1
	v_sub_f32_e32 v36, v146, v4
	v_add_f32_e32 v27, 1.0, v27
	v_add_f32_dpp v28, v28, v28 row_ror:4 row_mask:0xf bank_mask:0xf bound_ctrl:1
	v_rcp_f32_e32 v27, v27
	v_lshlrev_b32_e32 v26, 16, v26
	v_add_f32_dpp v28, v28, v28 row_ror:8 row_mask:0xf bank_mask:0xf bound_ctrl:1
	v_add_f32_e32 v26, v148, v26
	v_readlane_b32 s31, v28, 16
	v_readlane_b32 s34, v28, 48
	v_readlane_b32 s28, v28, 0
	v_readlane_b32 s29, v28, 32
	v_mov_b32_e32 v28, s31
	v_mov_b32_e32 v29, s34
	v_pk_add_f32 v[28:29], s[28:29], v[28:29]
	v_mul_f32_e32 v40, v36, v27
	v_add_f32_e32 v28, v28, v29
	v_sqrt_f32_e32 v28, v28
	v_add_f32_e32 v27, 1.0, v37
	v_rcp_f32_e32 v27, v27
	v_mul_f32_e32 v26, 0xbfb8aa3b, v26
	v_xor_b32_e32 v28, 0x80000000, v28
	v_min_f32_e32 v28, 0xab8cbccc, v28
	v_rcp_f32_e32 v28, v28
	v_add_f32_e32 v29, -1.0, v27
	v_fma_f32 v29, v151, v29, 1.0
	v_mul_f32_e32 v36, v29, v5
	v_mul_f32_e32 v37, v39, v28
	v_lshlrev_b32_e32 v28, 16, v38
	v_lshlrev_b32_e32 v38, 16, v136
	v_mul_f32_e32 v5, v36, v38
	v_mul_f32_e32 v29, v152, v5
	v_exp_f32_e32 v26, v26
	v_xor_b32_e32 v83, 0x80000000, v37
	v_mov_b32_dpp v29, v29 quad_perm:[1,0,3,2] row_mask:0xf bank_mask:0xf bound_ctrl:1
	v_fmac_f32_e32 v29, v152, v5
	v_add_f32_e32 v26, 1.0, v26
	v_rcp_f32_e32 v26, v26
	v_add_f32_dpp v5, v29, v29 quad_perm:[2,3,0,1] row_mask:0xf bank_mask:0xf bound_ctrl:1
	v_pk_mul_f32 v[26:27], v[26:27], v[82:83]
	s_nop 0
	v_add_f32_dpp v5, v5, v5 row_ror:4 row_mask:0xf bank_mask:0xf bound_ctrl:1
	s_nop 1
	v_add_f32_dpp v5, v5, v5 row_ror:8 row_mask:0xf bank_mask:0xf bound_ctrl:1
	s_nop 0
	v_readlane_b32 s29, v5, 16
	v_readlane_b32 s28, v5, 0
	s_nop 0
	v_mov_b32_e32 v29, s29
	v_readlane_b32 s29, v5, 48
	v_add_f32_e32 v41, s28, v29
	v_readlane_b32 s28, v5, 32
	v_mov_b32_e32 v5, s29
	s_nop 0
	v_add_f32_e32 v5, s28, v5
	v_pk_add_f32 v[4:5], v[40:41], v[4:5]
.LBB0_3316:
	v_add_u32_e32 v29, s33, v111
	ds_write_b32 v29, v26 offset:62464
	v_cvt_pk_bf16_f32 v4, v4, v2
	ds_write_b16 v45, v4 offset:144
	v_cvt_pk_bf16_f32 v4, v28, v2
	ds_write_b16 v46, v4 offset:144
	s_and_saveexec_b64 s[28:29], s[26:27]
	s_lshl_b32 s31, s55, 2
	s_add_i32 s31, s30, s31
	v_mov_b32_e32 v4, s31
	ds_write_b32 v4, v5 offset:8
	s_or_b64 exec, exec, s[28:29]
	v_mov_b32_e32 v40, 0
	s_cmp_ge_i32 s67, s24
	v_mov_b32_e32 v39, 0
	v_mov_b32_e32 v4, 0
	v_mov_b32_e32 v5, 0
	v_mov_b32_e32 v28, 0
	v_mov_b32_e32 v29, 0
	v_mov_b32_e32 v47, 0
	v_mov_b32_e32 v41, 0
	s_cbranch_scc1 .LBB0_3320
	v_mov_b32_e32 v28, v228
	v_mov_b32_e32 v29, v229
	v_mov_b32_e32 v39, v230
	v_mov_b32_e32 v3, v231
	v_lshlrev_b32_e32 v5, 16, v141
	v_mul_f32_e32 v43, v150, v5
	v_lshlrev_b32_e32 v29, 16, v29
	v_add_f32_e32 v29, v153, v29
	v_mul_f32_e32 v40, v43, v43
	v_mul_f32_e32 v29, 0xbfb8aa3b, v29
	v_exp_f32_e32 v29, v29
	v_mov_b32_dpp v40, v40 quad_perm:[1,0,3,2] row_mask:0xf bank_mask:0xf bound_ctrl:1
	v_fmac_f32_e32 v40, v43, v43
	v_lshlrev_b32_e32 v39, 16, v39
	v_add_f32_e32 v39, v149, v39
	v_add_f32_dpp v40, v40, v40 quad_perm:[2,3,0,1] row_mask:0xf bank_mask:0xf bound_ctrl:1
	v_add_f32_e32 v29, 1.0, v29
	v_mul_f32_e32 v39, 0xbfb8aa3b, v39
	v_add_f32_dpp v40, v40, v40 row_ror:4 row_mask:0xf bank_mask:0xf bound_ctrl:1
	v_rcp_f32_e32 v29, v29
	v_exp_f32_e32 v39, v39
	v_add_f32_dpp v40, v40, v40 row_ror:8 row_mask:0xf bank_mask:0xf bound_ctrl:1
	v_lshlrev_b32_e32 v4, 16, v145
	v_readlane_b32 s24, v40, 16
	v_readlane_b32 s31, v40, 48
	v_readlane_b32 s28, v40, 0
	v_readlane_b32 s29, v40, 32
	v_mov_b32_e32 v40, s24
	v_mov_b32_e32 v41, s31
	v_pk_add_f32 v[40:41], s[28:29], v[40:41]
	v_sub_f32_e32 v42, v147, v4
	v_add_f32_e32 v40, v40, v41
	v_sqrt_f32_e32 v40, v40
	v_mul_f32_e32 v42, v42, v29
	v_add_f32_e32 v29, 1.0, v39
	v_rcp_f32_e32 v29, v29
	v_xor_b32_e32 v39, 0x80000000, v40
	v_min_f32_e32 v39, 0xab8cbccc, v39
	v_rcp_f32_e32 v40, v39
	v_add_f32_e32 v39, -1.0, v29
	v_fma_f32 v39, v151, v39, 1.0
	v_lshlrev_b32_e32 v28, 16, v28
	v_mul_f32_e32 v39, v39, v5
	v_lshlrev_b32_e32 v41, 16, v139
	v_add_f32_e32 v28, v148, v28
	v_lshlrev_b32_e32 v47, 16, v3
	v_mul_f32_e32 v3, v39, v41
	v_mul_f32_e32 v28, 0xbfb8aa3b, v28
	v_mul_f32_e32 v5, v152, v3
	v_exp_f32_e32 v28, v28
	v_mul_f32_e32 v40, v43, v40
	v_mov_b32_dpp v5, v5 quad_perm:[1,0,3,2] row_mask:0xf bank_mask:0xf bound_ctrl:1
	v_fmac_f32_e32 v5, v152, v3
	v_add_f32_e32 v28, 1.0, v28
	v_rcp_f32_e32 v28, v28
	v_add_f32_dpp v3, v5, v5 quad_perm:[2,3,0,1] row_mask:0xf bank_mask:0xf bound_ctrl:1
	v_xor_b32_e32 v83, 0x80000000, v40
	v_pk_mul_f32 v[28:29], v[28:29], v[82:83]
	v_add_f32_dpp v3, v3, v3 row_ror:4 row_mask:0xf bank_mask:0xf bound_ctrl:1
	s_nop 1
	v_add_f32_dpp v3, v3, v3 row_ror:8 row_mask:0xf bank_mask:0xf bound_ctrl:1
	s_nop 0
	v_readlane_b32 s28, v3, 16
	v_readlane_b32 s24, v3, 0
	s_nop 0
	v_mov_b32_e32 v5, s28
	v_readlane_b32 s28, v3, 48
	v_add_f32_e32 v43, s24, v5
	v_readlane_b32 s24, v3, 32
	v_mov_b32_e32 v3, s28
	s_nop 0
	v_add_f32_e32 v5, s24, v3
	v_pk_add_f32 v[4:5], v[42:43], v[4:5]

.LBB0_3328:
	s_andn2_b64 vcc, exec, s[34:35]
	s_cbranch_vccnz .LBB0_3364
	v_add3_u32 v38, s40, v5, v4
	s_nop 8
	ds_read_b128 v[22:25], v38
	v_add3_u32 v4, s41, v5, v4
	ds_read_b128 v[26:29], v4
	ds_read_b128 v[40:43], v38 offset:32
	ds_read_b128 v[44:47], v4 offset:32
	v_lshlrev_b32_e32 v5, 2, v39
	s_mov_b64 s[34:35], -1
	s_and_b64 vcc, exec, s[60:61]
	ds_read_b128 v[176:179], v38 offset:64
	ds_read_b128 v[180:183], v4 offset:64
	ds_read_b128 v[184:187], v38 offset:96
	ds_read_b128 v[188:191], v4 offset:96
	s_waitcnt lgkmcnt(6)
	v_mfma_f32_32x32x16_bf16 v[22:37], v[22:25], v[26:29], 0
	s_waitcnt lgkmcnt(4)
	v_mfma_f32_32x32x16_bf16 v[22:37], v[40:43], v[44:47], v[22:37]
	s_waitcnt lgkmcnt(2)
	v_mfma_f32_32x32x16_bf16 v[22:37], v[176:179], v[180:183], v[22:37]
	v_lshl_add_u32 v4, v3, 1, s44
	s_waitcnt lgkmcnt(0)
	v_mfma_f32_32x32x16_bf16 v[22:37], v[184:187], v[188:191], v[22:37]
	s_cbranch_vccz .Lst3_nab_1
	v_cndmask_b32_e64 v38, 1, 0, s[4:5]
	v_sub_u32_e32 v40, v3, v5
	v_lshl_add_u32 v208, v39, 8, v4
	v_sub_u32_e32 v209, v40, v38
	v_lshl_add_u32 v208, v39, 6, v208
	s_nop 7
	s_nop 3
	v_cmp_gt_i32_e64 vcc, 0, v209
	v_cmp_gt_i32_e64 s[34:35], 1, v209
	v_cmp_gt_i32_e64 s[64:65], 2, v209
	v_cndmask_b32_e64 v38, 0, v22, vcc
	v_cvt_pk_bf16_f32 v38, v38, v2
	ds_write_b16 v208, v38
	v_cmp_gt_i32_e64 vcc, 3, v209
	v_cndmask_b32_e64 v40, 0, v23, s[34:35]
	v_cvt_pk_bf16_f32 v40, v40, v2
	ds_write_b16 v208, v40 offset:80
	v_cmp_gt_i32_e64 s[34:35], 8, v209
	v_cndmask_b32_e64 v41, 0, v24, s[64:65]
	v_cvt_pk_bf16_f32 v41, v41, v2
	ds_write_b16 v208, v41 offset:160
	v_cmp_gt_i32_e64 s[64:65], 9, v209
	v_cndmask_b32_e64 v42, 0, v25, vcc
	v_cvt_pk_bf16_f32 v42, v42, v2
	ds_write_b16 v208, v42 offset:240
	v_cmp_gt_i32_e64 vcc, 10, v209
	v_cndmask_b32_e64 v38, 0, v26, s[34:35]
	v_cvt_pk_bf16_f32 v38, v38, v2
	ds_write_b16 v208, v38 offset:640
	v_cmp_gt_i32_e64 s[34:35], 11, v209
	v_cndmask_b32_e64 v40, 0, v27, s[64:65]
	v_cvt_pk_bf16_f32 v40, v40, v2
	ds_write_b16 v208, v40 offset:720
	v_cmp_gt_i32_e64 s[64:65], 16, v209
	v_cndmask_b32_e64 v41, 0, v28, vcc
	v_cvt_pk_bf16_f32 v41, v41, v2
	ds_write_b16 v208, v41 offset:800
	v_cmp_gt_i32_e64 vcc, 17, v209
	v_cndmask_b32_e64 v42, 0, v29, s[34:35]
	v_cvt_pk_bf16_f32 v42, v42, v2
	ds_write_b16 v208, v42 offset:880
	v_cmp_gt_i32_e64 s[34:35], 18, v209
	v_cndmask_b32_e64 v38, 0, v30, s[64:65]
	v_cvt_pk_bf16_f32 v38, v38, v2
	ds_write_b16 v208, v38 offset:1280
	v_cmp_gt_i32_e64 s[64:65], 19, v209
	v_cndmask_b32_e64 v40, 0, v31, vcc
	v_cvt_pk_bf16_f32 v40, v40, v2
	ds_write_b16 v208, v40 offset:1360
	v_cmp_gt_i32_e64 vcc, 24, v209
	v_cndmask_b32_e64 v41, 0, v32, s[34:35]
	v_cvt_pk_bf16_f32 v41, v41, v2
	ds_write_b16 v208, v41 offset:1440
	v_cmp_gt_i32_e64 s[34:35], 25, v209
	v_cndmask_b32_e64 v42, 0, v33, s[64:65]
	v_cvt_pk_bf16_f32 v42, v42, v2
	ds_write_b16 v208, v42 offset:1520
	v_cmp_gt_i32_e64 s[64:65], 26, v209
	v_cndmask_b32_e64 v38, 0, v34, vcc
	v_cvt_pk_bf16_f32 v38, v38, v2
	ds_write_b16 v208, v38 offset:1920
	v_cmp_gt_i32_e64 vcc, 27, v209
	v_cndmask_b32_e64 v40, 0, v35, s[34:35]
	v_cvt_pk_bf16_f32 v40, v40, v2
	ds_write_b16 v208, v40 offset:2000
	v_cndmask_b32_e64 v41, 0, v36, s[64:65]
	v_cvt_pk_bf16_f32 v41, v41, v2
	ds_write_b16 v208, v41 offset:2080
	v_cndmask_b32_e64 v42, 0, v37, vcc
	v_cvt_pk_bf16_f32 v42, v42, v2
	ds_write_b16 v208, v42 offset:2160
	s_branch .Lst3_join_1
.Lst3_nab_1:
	v_sub_u32_e32 v209, v3, v5
	v_lshlrev_b32_e32 v40, 2, v3
	v_lshl_add_u32 v208, v39, 9, v40
	s_nop 7
	s_nop 5
	v_cmp_lt_i32_e64 vcc, 0, v209
	v_cmp_lt_i32_e64 s[34:35], 1, v209
	v_cmp_lt_i32_e64 s[64:65], 2, v209
	v_cndmask_b32_e64 v38, 0, v22, vcc
	ds_write_b32 v208, v38 offset:58368
	v_cmp_lt_i32_e64 vcc, 3, v209
	v_cndmask_b32_e64 v40, 0, v23, s[34:35]
	ds_write_b32 v208, v40 offset:58496
	v_cmp_lt_i32_e64 s[34:35], 8, v209
	v_cndmask_b32_e64 v41, 0, v24, s[64:65]
	ds_write_b32 v208, v41 offset:58624
	v_cmp_lt_i32_e64 s[64:65], 9, v209
	v_cndmask_b32_e64 v42, 0, v25, vcc
	ds_write_b32 v208, v42 offset:58752
	v_cmp_lt_i32_e64 vcc, 10, v209
	v_cndmask_b32_e64 v38, 0, v26, s[34:35]
	ds_write_b32 v208, v38 offset:59392
	v_cmp_lt_i32_e64 s[34:35], 11, v209
	v_cndmask_b32_e64 v40, 0, v27, s[64:65]
	ds_write_b32 v208, v40 offset:59520
	v_cmp_lt_i32_e64 s[64:65], 16, v209
	v_cndmask_b32_e64 v41, 0, v28, vcc
	ds_write_b32 v208, v41 offset:59648
	v_cmp_lt_i32_e64 vcc, 17, v209
	v_cndmask_b32_e64 v42, 0, v29, s[34:35]
	ds_write_b32 v208, v42 offset:59776
	v_cmp_lt_i32_e64 s[34:35], 18, v209
	v_cndmask_b32_e64 v38, 0, v30, s[64:65]
	ds_write_b32 v208, v38 offset:60416
	v_cmp_lt_i32_e64 s[64:65], 19, v209
	v_cndmask_b32_e64 v40, 0, v31, vcc
	ds_write_b32 v208, v40 offset:60544
	v_cmp_lt_i32_e64 vcc, 24, v209
	v_cndmask_b32_e64 v41, 0, v32, s[34:35]
	ds_write_b32 v208, v41 offset:60672
	v_cmp_lt_i32_e64 s[34:35], 25, v209
	v_cndmask_b32_e64 v42, 0, v33, s[64:65]
	ds_write_b32 v208, v42 offset:60800
	v_cmp_lt_i32_e64 s[64:65], 26, v209
	v_cndmask_b32_e64 v38, 0, v34, vcc
	ds_write_b32 v208, v38 offset:61440
	v_cmp_lt_i32_e64 vcc, 27, v209
	v_cndmask_b32_e64 v40, 0, v35, s[34:35]
	ds_write_b32 v208, v40 offset:61568
	v_cndmask_b32_e64 v41, 0, v36, s[64:65]
	ds_write_b32 v208, v41 offset:61696
	v_cndmask_b32_e64 v42, 0, v37, vcc
	ds_write_b32 v208, v42 offset:61824
.Lst3_join_1:
.LBB0_3364:
	s_andn2_b64 vcc, exec, s[2:3]
	s_waitcnt lgkmcnt(0)
	s_barrier
	s_cbranch_vccnz .LBB0_3366
	v_mov_b32_e32 v3, v106
	s_add_i32 s34, s23, 0
	v_and_b32_e32 v4, 31, v3
	v_ashrrev_i32_e32 v5, 5, v3
	v_mul_u32_u24_e32 v38, 0x50, v4
	v_lshlrev_b32_e32 v39, 4, v5
	v_add3_u32 v46, 0, v38, v39
	v_lshrrev_b32_e32 v38, 2, v3
	v_and_b32_e32 v39, 16, v3
	v_lshlrev_b32_e32 v3, 2, v3
	v_and_b32_e32 v38, 0xffffffb, v38
	v_and_b32_e32 v3, 12, v3
	v_or3_b32 v3, v39, v3, s54
	v_mul_lo_u32 v44, v38, s47
	ds_read_b128 v[38:41], v46 offset:50688
	v_lshlrev_b32_e32 v3, 1, v3
	v_add3_u32 v47, s34, v3, v44
	v_add3_u32 v3, s34, v44, v3
	ds_read_b64_tr_b16 v[42:43], v47
	ds_read_b64_tr_b16 v[44:45], v3 offset:576
	ds_read_b128 v[208:211], v46 offset:50720
	ds_read_b64_tr_b16 v[212:213], v47 offset:2304
	ds_read_b64_tr_b16 v[214:215], v3 offset:2880
	s_waitcnt lgkmcnt(3)
	v_mfma_f32_32x32x16_bf16 v[22:37], v[38:41], v[42:45], v[22:37]
	v_lshlrev_b32_e32 v3, 10, v5
	v_lshlrev_b32_e32 v4, 2, v4
	v_add3_u32 v3, s53, v3, v4
	v_add_u32_e32 v4, 0xf400, v3
	s_waitcnt lgkmcnt(0)
	v_mfma_f32_32x32x16_bf16 v[22:37], v[208:211], v[212:215], v[22:37]
	s_nop 11
	ds_write2st64_b32 v3, v22, v23 offset0:244 offset1:245
	ds_write2st64_b32 v3, v24, v25 offset0:246 offset1:247
	ds_write2st64_b32 v3, v26, v27 offset0:252 offset1:253
	ds_write2st64_b32 v3, v28, v29 offset0:254 offset1:255
	ds_write2st64_b32 v4, v30, v31 offset0:16 offset1:17
	ds_write2st64_b32 v4, v32, v33 offset0:18 offset1:19
	ds_write2st64_b32 v4, v34, v35 offset0:24 offset1:25
	ds_write2st64_b32 v4, v36, v37 offset0:26 offset1:27

.LBB0_3371:
	v_mov_b32_e32 v4, v106
	s_waitcnt lgkmcnt(0)
	s_barrier
	s_mov_b64 s[30:31], -1
	v_and_b32_e32 v3, 31, v4
	s_and_b64 vcc, exec, s[6:7]
	s_cbranch_vccz .LBB0_3375
	v_mov_b64_e32 v[52:53], v[20:21]
	s_and_b64 vcc, exec, s[28:29]
	v_mov_b64_e32 v[50:51], v[18:19]
	v_mov_b64_e32 v[48:49], v[16:17]
	v_mov_b64_e32 v[46:47], v[14:15]
	v_mov_b64_e32 v[44:45], v[12:13]
	v_mov_b64_e32 v[42:43], v[10:11]
	v_mov_b64_e32 v[40:41], v[8:9]
	v_mov_b64_e32 v[38:39], v[6:7]
	s_cbranch_vccnz .LBB0_3374
	v_lshl_add_u32 v5, v3, 2, s45
	v_and_b32_e32 v83, 16, v4
	v_lshlrev_b32_e32 v86, 2, v4
	ds_read_b32 v38, v5
	v_lshrrev_b32_e32 v5, 2, v4
	v_and_or_b32 v83, v86, 12, v83
	v_and_b32_e32 v5, 0xffffffb, v5
	v_or_b32_e32 v86, s37, v83
	v_or_b32_e32 v83, s54, v83
	v_lshlrev_b32_e32 v86, 1, v86
	v_lshlrev_b32_e32 v83, 1, v83
	v_mul_lo_u32 v5, v5, s47
	v_add3_u32 v102, 0, v86, v5
	v_add3_u32 v83, 0, v83, v5
	ds_read_b64_tr_b16 v[94:95], v102 offset:32256
	ds_read_b64_tr_b16 v[96:97], v102 offset:32832
	ds_read_b64_tr_b16 v[98:99], v83 offset:18432
	ds_read_b64_tr_b16 v[100:101], v83 offset:19008
	s_add_i32 s25, s23, 0
	v_add3_u32 v5, s25, v86, v5
	ds_read_b64_tr_b16 v[208:209], v5
	ds_read_b64_tr_b16 v[210:211], v5 offset:576
	ds_read_b64_tr_b16 v[212:213], v83 offset:23040
	ds_read_b64_tr_b16 v[214:215], v83 offset:23616
	ds_read_b64_tr_b16 v[216:217], v102 offset:34560
	ds_read_b64_tr_b16 v[218:219], v102 offset:35136
	ds_read_b64_tr_b16 v[220:221], v83 offset:20736
	ds_read_b64_tr_b16 v[222:223], v83 offset:21312
	s_waitcnt lgkmcnt(12)
	v_pk_mul_f32 v[52:53], v[20:21], v[38:39] op_sel_hi:[1,0]
	v_pk_mul_f32 v[50:51], v[18:19], v[38:39] op_sel_hi:[1,0]
	v_pk_mul_f32 v[48:49], v[16:17], v[38:39] op_sel_hi:[1,0]
	v_pk_mul_f32 v[46:47], v[14:15], v[38:39] op_sel_hi:[1,0]
	v_pk_mul_f32 v[44:45], v[12:13], v[38:39] op_sel_hi:[1,0]
	v_pk_mul_f32 v[42:43], v[10:11], v[38:39] op_sel_hi:[1,0]
	v_pk_mul_f32 v[40:41], v[8:9], v[38:39] op_sel_hi:[1,0]
	v_pk_mul_f32 v[38:39], v[6:7], v[38:39] op_sel_hi:[1,0]
	s_waitcnt lgkmcnt(8)
	ds_read_b64_tr_b16 v[224:225], v5 offset:2304
	ds_read_b64_tr_b16 v[226:227], v5 offset:2880
	ds_read_b64_tr_b16 v[228:229], v83 offset:25344
	ds_read_b64_tr_b16 v[230:231], v83 offset:25920
	v_mfma_f32_32x32x16_bf16 v[38:53], v[94:97], v[98:101], v[38:53]
	s_waitcnt lgkmcnt(8)
	v_mfma_f32_32x32x16_bf16 v[38:53], v[208:211], v[212:215], v[38:53]
	s_waitcnt lgkmcnt(4)
	v_mfma_f32_32x32x16_bf16 v[38:53], v[216:219], v[220:223], v[38:53]
	s_waitcnt lgkmcnt(0)
	v_mfma_f32_32x32x16_bf16 v[38:53], v[224:227], v[228:231], v[38:53]

.LBB0_3375:
	s_andn2_b64 vcc, exec, s[30:31]
	s_cbranch_vccnz .LBB0_3377
	v_ashrrev_i32_e32 v5, 5, v4
	s_nop 7
	v_lshrrev_b32_e32 v40, 2, v4
	v_and_b32_e32 v41, 16, v4
	v_lshlrev_b32_e32 v4, 2, v4
	v_and_b32_e32 v4, 12, v4
	v_and_b32_e32 v40, 0xffffffb, v40
	v_or3_b32 v4, v41, v4, s54
	v_lshlrev_b32_e32 v4, 1, v4
	v_mul_lo_u32 v51, v40, s47
	v_mul_u32_u24_e32 v38, 0x50, v3
	v_lshlrev_b32_e32 v39, 4, v5
	v_add3_u32 v52, 0, v4, v51
	v_add3_u32 v50, 0, v38, v39
	ds_read_b64_tr_b16 v[38:39], v52 offset:32256
	ds_read_b64_tr_b16 v[40:41], v52 offset:32832
	ds_read_b128 v[42:45], v50 offset:53248
	ds_read_b128 v[46:49], v50 offset:53280
	s_add_i32 s23, s23, 0
	v_add3_u32 v4, s23, v4, v51
	ds_read_b128 v[208:211], v50 offset:55808
	ds_read_b64_tr_b16 v[212:213], v4
	ds_read_b64_tr_b16 v[214:215], v4 offset:576
	ds_read_b64_tr_b16 v[216:217], v52 offset:34560
	ds_read_b64_tr_b16 v[218:219], v52 offset:35136
	ds_read_b128 v[220:223], v50 offset:55840
	ds_read_b64_tr_b16 v[224:225], v4 offset:2304
	ds_read_b64_tr_b16 v[226:227], v4 offset:2880
	v_lshlrev_b32_e32 v3, 2, v3
	s_waitcnt lgkmcnt(9)
	v_mfma_f32_32x32x16_bf16 v[22:37], v[42:45], v[38:41], v[22:37]
	s_waitcnt lgkmcnt(5)
	v_mfma_f32_32x32x16_bf16 v[22:37], v[208:211], v[212:215], v[22:37]
	s_waitcnt lgkmcnt(3)
	v_mfma_f32_32x32x16_bf16 v[22:37], v[46:49], v[216:219], v[22:37]
	v_lshlrev_b32_e32 v4, 10, v5
	v_add3_u32 v3, s58, v4, v3
	s_waitcnt lgkmcnt(0)
	v_mfma_f32_32x32x16_bf16 v[22:37], v[220:223], v[224:227], v[22:37]
	v_mov_b64_e32 v[52:53], v[20:21]
	v_mov_b64_e32 v[50:51], v[18:19]
	v_mov_b64_e32 v[48:49], v[16:17]
	v_mov_b64_e32 v[46:47], v[14:15]
	v_mov_b64_e32 v[44:45], v[12:13]
	v_mov_b64_e32 v[42:43], v[10:11]
	v_mov_b64_e32 v[40:41], v[8:9]
	v_mov_b64_e32 v[38:39], v[6:7]
	s_nop 3
	ds_write2st64_b32 v3, v22, v23 offset1:1
	ds_write2st64_b32 v3, v24, v25 offset0:2 offset1:3
	ds_write2st64_b32 v3, v26, v27 offset0:8 offset1:9
	ds_write2st64_b32 v3, v28, v29 offset0:10 offset1:11
	ds_write2st64_b32 v3, v30, v31 offset0:16 offset1:17
	ds_write2st64_b32 v3, v32, v33 offset0:18 offset1:19
	ds_write2st64_b32 v3, v34, v35 offset0:24 offset1:25
	ds_write2st64_b32 v3, v36, v37 offset0:26 offset1:27

.LBB0_3391:
	s_or_b64 exec, exec, s[28:29]
	v_cndmask_b32_e64 v3, 0, 1, s[0:1]
	v_cmp_ne_u32_e64 s[28:29], 1, v3
	s_andn2_b64 vcc, exec, s[0:1]
	s_cbranch_vccz .LBB0_3323
	s_branch .LBB0_3324
.LBB0_3421:
	s_add_i32 s34, s28, s50
	s_ashr_i32 s35, s34, 31
	v_mad_i64_i32 v[4:5], s[64:65], s34, v131, v[90:91]
	v_add_co_u32_e32 v42, vcc, 0x1000, v4
	s_lshl_b64 s[34:35], s[34:35], 12
	s_nop 0
	v_addc_co_u32_e32 v43, vcc, 0, v5, vcc
	global_load_ushort v132, v[4:5], off
	global_load_ushort v133, v[4:5], off offset:2048
	global_load_ushort v137, v[42:43], off
	v_lshl_add_u64 v[4:5], v[92:93], 0, s[34:35]
	global_load_dword v142, v[4:5], off
	s_or_b32 s29, s28, 1
	s_cmp_ge_i32 s29, s57
	s_cbranch_scc1 .LBB0_3382
